# attention loop: exp/rowsum interleaved into MFMA stream (step A), counted lgkmcnt waits, packed f32 ops split, row-max check skipped once Cauchy-Schwarz bound proves no overflow; P5: lean epilogue + c
# speedup vs baseline: 1.0545x; 1.0385x over previous
.LBB0_443:
	s_lshr_b32 s2, s15, 6
	s_ashr_i32 s78, s15, 8
	s_add_i32 s2, s2, s78
	s_and_b32 s10, s2, 3
	s_mul_i32 s3, s78, 23
	s_not_b32 s2, s10
	s_add_i32 s3, s3, s15
	s_lshl_b32 s4, s2, 1
	s_lshl_b32 s2, s78, 5
	s_and_b32 s48, s3, 63
	s_ashr_i32 s3, s2, 31
	s_lshl_b32 s34, s48, 7
	s_lshl_b64 s[2:3], s[2:3], 2
	s_add_u32 s2, s1, s2
	s_addc_u32 s3, s6, s3
	s_lshl_b32 s5, s10, 4
	v_mov_b32_e32 v0, s5
	global_load_dwordx4 v[2:5], v0, s[2:3]
	global_load_dwordx4 v[6:9], v0, s[2:3] offset:64
	v_cvt_f32_i32_e32 v0, s4
	s_waitcnt vmcnt(1)
	v_mov_b32_e32 v10, v2
	s_waitcnt vmcnt(0)
	v_mov_b32_e32 v11, v6
	v_mov_b32_e32 v6, v3
	v_mov_b32_e32 v2, v4
	v_mov_b32_e32 v3, v8
	v_mov_b32_e32 v8, v5
	v_pk_add_f32 v[4:5], v[10:11], v[6:7]
	v_pk_add_f32 v[2:3], v[2:3], v[8:9]
	v_mul_f32_e32 v4, v4, v5
	v_mul_f32_e32 v2, v2, v3
	v_mul_f32_e32 v3, 0x4f800000, v4
	v_cmp_gt_f32_e32 vcc, s35, v4
	v_mul_f32_e32 v5, 0x4f800000, v2
	v_cmp_gt_f32_e64 s[2:3], s35, v2
	v_cndmask_b32_e32 v4, v4, v3, vcc
	v_sqrt_f32_e32 v6, v4
	v_cndmask_b32_e64 v2, v2, v5, s[2:3]
	v_sqrt_f32_e32 v5, v2
	v_exp_f32_e32 v3, v0
	v_add_u32_e32 v0, -1, v6
	v_fma_f32 v10, -v0, v6, v4
	v_add_u32_e32 v8, -1, v5
	v_add_u32_e32 v7, 1, v6
	v_fma_f32 v12, -v8, v5, v2
	v_cmp_ge_f32_e64 s[4:5], 0, v10
	v_add_u32_e32 v9, 1, v5
	v_fma_f32 v11, -v7, v6, v4
	v_cndmask_b32_e64 v0, v6, v0, s[4:5]
	v_cmp_ge_f32_e64 s[4:5], 0, v12
	v_fma_f32 v13, -v9, v5, v2
	s_nop 0
	v_cndmask_b32_e64 v5, v5, v8, s[4:5]
	v_cmp_lt_f32_e64 s[4:5], 0, v11
	s_nop 1
	v_cndmask_b32_e64 v0, v0, v7, s[4:5]
	v_cmp_lt_f32_e64 s[4:5], 0, v13
	v_mul_f32_e32 v6, 0x37800000, v0
	v_cndmask_b32_e32 v0, v0, v6, vcc
	v_cndmask_b32_e64 v5, v5, v9, s[4:5]
	v_mul_f32_e32 v7, 0x37800000, v5
	v_cmp_class_f32_e32 vcc, v4, v222
	v_cndmask_b32_e64 v5, v5, v7, s[2:3]
	s_nop 0
	v_cndmask_b32_e32 v0, v0, v4, vcc
	v_cmp_class_f32_e32 vcc, v2, v222
	s_nop 1
	v_cndmask_b32_e32 v2, v5, v2, vcc
	v_max3_f32 v0, v0, 0, v2
	v_mul_f32_e32 v2, 0x3f828f5c, v0
	v_cmp_gt_f32_e32 vcc, 0x42200000, v2
	s_cmp_lg_u64 vcc, 0
	s_cselect_b32 s98, 1, 0
	s_mov_b32 s99, 0
	v_pk_mul_f32 v[200:201], v[2:3], s[8:9]
	s_nop 0
	v_add_f32_e32 v0, 0x432a0000, v200
	v_div_scale_f32 v2, s[2:3], v201, v201, v0
	v_rcp_f32_e32 v3, v2
	v_div_scale_f32 v4, vcc, v0, v201, v0
	s_mov_b32 s2, 0x46000000
	v_fma_f32 v5, -v2, v3, 1.0
	v_fmac_f32_e32 v3, v5, v3
	v_mul_f32_e32 v5, v4, v3
	v_fma_f32 v6, -v2, v5, v4
	v_fmac_f32_e32 v5, v6, v3
	v_fma_f32 v2, -v2, v5, v4
	v_div_fmas_f32 v2, v2, v3, v5
	v_div_fixup_f32 v0, v2, v201, v0
	v_cvt_i32_f32_e32 v2, v0
	v_cmp_gt_f32_e32 vcc, s2, v0
	v_readfirstlane_b32 s2, v2
	s_add_i32 s4, s2, 1
	s_and_b64 s[2:3], vcc, exec
	s_cselect_b32 s2, s4, 0x2000
	s_sub_i32 s3, s34, s2
	s_add_i32 s2, s2, s34
	s_addk_i32 s2, 0x7f
	s_max_i32 s3, s3, 0
	s_min_i32 s2, s2, 0x1fff
	s_lshr_b32 s33, s3, 6
	s_ashr_i32 s4, s2, 6
	s_sub_i32 s2, s4, s33
	s_bitcmp1_b32 s2, 0
	s_cselect_b64 s[2:3], -1, 0
	s_and_b64 vcc, exec, s[2:3]
	s_cbranch_vccnz .LBB0_449
	s_cmpk_gt_i32 s4, 0x7e
	s_mov_b64 s[2:3], -1
	s_cbranch_scc0 .LBB0_446
	s_add_i32 s5, s33, -1
	s_mov_b64 s[2:3], 0

.LBB0_454:
	s_mov_b64 s[2:3], 0
	s_cmp_lg_u32 s99, 0
	s_cbranch_scc1 .LBB0_456
	v_max3_f32 v102, v66, v67, v82
	v_max3_f32 v103, v68, v69, v83
	s_nop 0
	v_max3_f32 v102, v102, v84, v85
	v_max3_f32 v103, v103, v72, v73
	s_nop 0
	v_max3_f32 v102, v102, v70, v71
	v_max3_f32 v103, v103, v88, v89
	s_nop 0
	v_max3_f32 v102, v102, v86, v87
	v_max3_f32 v103, v103, v76, v77
	s_nop 0
	v_max3_f32 v102, v102, v74, v75
	v_max3_f32 v103, v103, v92, v93
	s_nop 0
	v_max3_f32 v102, v102, v90, v91
	v_max3_f32 v103, v103, v80, v81
	s_nop 0
	v_max3_f32 v102, v102, v78, v79
	v_max3_f32 v103, v103, v96, v97
	s_nop 0
	v_max3_f32 v102, v102, v94, v95
	s_nop 0
	v_max_f32_e32 v102, v102, v103
	s_nop 0
	v_mov_b32_e32 v103, v102
	s_nop 1
	v_permlane32_swap_b32 v102, v103
	s_nop 1
	s_nop 0
	v_max_f32_e32 v103, v103, v103
	v_max_f32_e32 v102, v102, v102
	v_max_f32_e32 v102, v102, v103
	v_cmp_lt_f32_e32 vcc, s56, v102
	s_cmp_lg_u64 vcc, 0
	s_cselect_b64 s[2:3], -1, 0
	s_cbranch_vccz .LBB0_456
	v_max_f32_e32 v0, v102, v102
	v_max_f32_e32 v102, 0, v0
	v_exp_f32_e64 v0, -v102
	v_pk_add_f32 v[66:67], v[66:67], v[102:103] op_sel_hi:[1,0] neg_lo:[0,1] neg_hi:[0,1]
	v_pk_add_f32 v[82:83], v[82:83], v[102:103] op_sel_hi:[1,0] neg_lo:[0,1] neg_hi:[0,1]
	v_pk_add_f32 v[68:69], v[68:69], v[102:103] op_sel_hi:[1,0] neg_lo:[0,1] neg_hi:[0,1]
	v_pk_add_f32 v[84:85], v[84:85], v[102:103] op_sel_hi:[1,0] neg_lo:[0,1] neg_hi:[0,1]
	v_pk_add_f32 v[70:71], v[70:71], v[102:103] op_sel_hi:[1,0] neg_lo:[0,1] neg_hi:[0,1]
	v_pk_add_f32 v[86:87], v[86:87], v[102:103] op_sel_hi:[1,0] neg_lo:[0,1] neg_hi:[0,1]
	v_pk_add_f32 v[72:73], v[72:73], v[102:103] op_sel_hi:[1,0] neg_lo:[0,1] neg_hi:[0,1]
	v_pk_add_f32 v[88:89], v[88:89], v[102:103] op_sel_hi:[1,0] neg_lo:[0,1] neg_hi:[0,1]
	v_pk_add_f32 v[74:75], v[74:75], v[102:103] op_sel_hi:[1,0] neg_lo:[0,1] neg_hi:[0,1]
	v_pk_add_f32 v[90:91], v[90:91], v[102:103] op_sel_hi:[1,0] neg_lo:[0,1] neg_hi:[0,1]
	v_pk_add_f32 v[76:77], v[76:77], v[102:103] op_sel_hi:[1,0] neg_lo:[0,1] neg_hi:[0,1]
	v_pk_add_f32 v[92:93], v[92:93], v[102:103] op_sel_hi:[1,0] neg_lo:[0,1] neg_hi:[0,1]
	v_pk_add_f32 v[78:79], v[78:79], v[102:103] op_sel_hi:[1,0] neg_lo:[0,1] neg_hi:[0,1]
	v_pk_add_f32 v[94:95], v[94:95], v[102:103] op_sel_hi:[1,0] neg_lo:[0,1] neg_hi:[0,1]
	v_pk_add_f32 v[80:81], v[80:81], v[102:103] op_sel_hi:[1,0] neg_lo:[0,1] neg_hi:[0,1]
	v_pk_add_f32 v[96:97], v[96:97], v[102:103] op_sel_hi:[1,0] neg_lo:[0,1] neg_hi:[0,1]
	v_add_f32_e32 v199, v199, v102
	v_mul_f32_e32 v198, v198, v0
.LBB0_456:
	s_mov_b32 s99, s98
	s_lshl_b32 s80, s10, 14
	v_add_u32_e32 v179, s80, v219
	v_add_u32_e32 v126, v179, v149
	ds_read_b128 v[102:105], v126 offset:49152
	ds_read_b128 v[118:121], v126 offset:53248
	ds_read_b128 v[122:125], v126 offset:57344
	ds_read_b128 v[228:231], v126 offset:61440
	s_add_i32 s78, s34, -1
	s_add_i32 s63, s60, 0x80
	s_lshl_b32 s79, s62, 14
	s_cmp_le_i32 s78, s48
	s_cselect_b64 s[4:5], -1, 0
	s_cmp_gt_i32 s78, s48
	s_waitcnt lgkmcnt(3)
	v_mfma_f32_32x32x16_bf16 v[50:65], v[102:105], v[98:101], v[50:65]
	v_exp_f32_e32 v66, v66
	v_exp_f32_e32 v249, v82
	v_add_u32_e32 v181, v179, v208
	ds_read_b128 v[102:105], v181 offset:49152
	s_waitcnt lgkmcnt(3)
	v_mfma_f32_32x32x16_bf16 v[34:49], v[118:121], v[98:101], v[34:49]
	v_add_f32_e32 v254, 0, v66
	v_add_f32_e32 v254, v249, v254
	v_exp_f32_e32 v67, v67
	v_exp_f32_e32 v250, v83
	ds_read_b128 v[232:235], v181 offset:53248
	s_waitcnt lgkmcnt(3)
	v_mfma_f32_32x32x16_bf16 v[18:33], v[122:125], v[98:101], v[18:33]
	v_add_f32_e32 v254, v67, v254
	v_add_f32_e32 v254, v250, v254
	v_exp_f32_e32 v68, v68
	v_exp_f32_e32 v195, v84
	ds_read_b128 v[126:129], v181 offset:57344
	s_waitcnt lgkmcnt(3)
	v_mfma_f32_32x32x16_bf16 v[2:17], v[228:231], v[98:101], v[2:17]
	v_add_f32_e32 v254, v68, v254
	v_add_f32_e32 v254, v195, v254
	v_exp_f32_e32 v69, v69
	v_exp_f32_e32 v251, v85
	ds_read_b128 v[118:121], v181 offset:61440
	s_waitcnt lgkmcnt(3)
	v_mfma_f32_32x32x16_bf16 v[50:65], v[102:105], v[106:109], v[50:65]
	v_add_f32_e32 v254, v69, v254
	v_add_f32_e32 v254, v251, v254
	v_exp_f32_e32 v70, v70
	v_exp_f32_e32 v252, v86
	v_add_u32_e32 v181, v179, v209
	ds_read_b128 v[122:125], v181 offset:49152
	s_waitcnt lgkmcnt(3)
	v_mfma_f32_32x32x16_bf16 v[34:49], v[232:235], v[106:109], v[34:49]
	s_cbranch_scc1 .LBB0_458
	s_add_i32 s78, s34, -3
	s_add_i32 s81, s60, 0x100
	s_cmp_lt_i32 s78, s39
	s_cselect_b32 s82, s63, s81
	s_ashr_i32 s83, s82, 31
	s_lshl_b64 s[82:83], s[82:83], 12
	s_add_i32 s78, s79, 0xffffc000
	s_cmp_lg_u32 s62, 0
	s_cselect_b32 s78, s78, 0x8000
	v_lshl_add_u64 v[98:99], v[202:203], 0, s[82:83]
	s_add_i32 s78, s7, s78
	v_lshl_add_u64 v[100:101], v[98:99], 0, s[30:31]
	s_mov_b32 m0, s78
	v_lshl_add_u64 v[98:99], v[98:99], 0, s[36:37]
	global_load_lds_dwordx4 v[100:101], off
	s_add_i32 m0, s78, 0x2000
	s_nop 0
	global_load_lds_dwordx4 v[98:99], off
.LBB0_458:
	s_add_i32 s78, s34, -4
	s_cmp_gt_i32 s78, s39
	s_cselect_b64 s[82:83], -1, 0
	v_cndmask_b32_e64 v200, v201, -v201, s[82:83]
	s_and_b64 s[82:83], s[82:83], exec
	s_cselect_b32 s82, s63, s60
	s_ashr_i32 s83, s82, 31
	s_lshl_b64 s[84:85], s[82:83], 1
	s_addk_i32 s80, 0xc000
	s_cmp_lg_u32 s10, 0
	s_cselect_b32 s80, s80, 0x8000
	s_add_i32 s80, s14, s80
	v_lshl_add_u64 v[98:99], v[204:205], 0, s[84:85]
	s_add_i32 m0, s80, 0xc000
	v_lshl_add_u64 v[100:101], v[206:207], 0, s[84:85]
	global_load_lds_dwordx4 v[98:99], off
	s_add_i32 m0, s80, 0xc400
	v_cvt_f32_i32_e32 v98, s82
	global_load_lds_dwordx4 v[100:101], off
	v_add_u32_e32 v183, s79, v218
	v_add_f32_e32 v98, v155, v98
	v_fma_f32 v224, v200, v98, -v199
	v_fma_f32 v98, 0, v200, v224
	v_add_f32_e32 v99, v200, v224
	v_fma_f32 v100, v200, s64, v224
	v_fma_f32 v101, v200, s65, v224
	v_fma_f32 v102, v200, s66, v224
	v_fma_f32 v103, v200, s67, v224
	v_mul_f32_e32 v240, 0x42000000, v200
	ds_read_b128 v[228:231], v181 offset:53248
	s_waitcnt lgkmcnt(3)
	v_mfma_f32_32x32x16_bf16 v[18:33], v[126:129], v[106:109], v[18:33]
	v_add_f32_e32 v254, v70, v254
	v_add_f32_e32 v254, v252, v254
	v_exp_f32_e32 v71, v71
	v_fma_f32 v104, v200, s68, v224
	v_fma_f32 v105, v200, s69, v224
	ds_read_b128 v[126:129], v181 offset:57344
	s_waitcnt lgkmcnt(3)
	v_mfma_f32_32x32x16_bf16 v[2:17], v[118:121], v[106:109], v[2:17]
	v_add_f32_e32 v254, v71, v254
	v_exp_f32_e32 v253, v87
	v_exp_f32_e32 v82, v72
	ds_read_b128 v[118:121], v181 offset:61440
	s_waitcnt lgkmcnt(3)
	v_mfma_f32_32x32x16_bf16 v[50:65], v[122:125], v[110:113], v[50:65]
	v_add_f32_e32 v254, v253, v254
	v_add_f32_e32 v254, v82, v254
	v_exp_f32_e32 v72, v88
	v_fma_f32 v106, v200, s70, v224
	v_fma_f32 v107, v200, s71, v224
	v_add_u32_e32 v179, v179, v226
	ds_read_b128 v[122:125], v179 offset:49152
	s_waitcnt lgkmcnt(3)
	v_mfma_f32_32x32x16_bf16 v[34:49], v[228:231], v[110:113], v[34:49]
	v_add_f32_e32 v254, v72, v254
	v_exp_f32_e32 v83, v73
	v_exp_f32_e32 v73, v89
	ds_read_b128 v[228:231], v179 offset:53248
	s_waitcnt lgkmcnt(3)
	v_mfma_f32_32x32x16_bf16 v[18:33], v[126:129], v[110:113], v[18:33]
	v_add_f32_e32 v254, v83, v254
	v_add_f32_e32 v254, v73, v254
	v_exp_f32_e32 v74, v74
	v_fma_f32 v108, v200, s72, v224
	v_fma_f32 v109, v200, s73, v224
	ds_read_b128 v[126:129], v179 offset:57344
	s_waitcnt lgkmcnt(3)
	v_mfma_f32_32x32x16_bf16 v[2:17], v[118:121], v[110:113], v[2:17]
	v_add_f32_e32 v254, v74, v254
	v_exp_f32_e32 v90, v90
	v_exp_f32_e32 v75, v75
	ds_read_b128 v[118:121], v179 offset:61440
	s_waitcnt lgkmcnt(3)
	v_mfma_f32_32x32x16_bf16 v[50:65], v[122:125], v[114:117], v[50:65]
	v_add_f32_e32 v254, v90, v254
	v_add_f32_e32 v254, v75, v254
	v_exp_f32_e32 v91, v91
	v_fma_f32 v110, v200, s74, v224
	v_fma_f32 v111, v200, s75, v224
	v_add_u32_e32 v112, v183, v149
	ds_read_b128 v[232:235], v112
	s_waitcnt lgkmcnt(3)
	v_mfma_f32_32x32x16_bf16 v[34:49], v[228:231], v[114:117], v[34:49]
	v_add_f32_e32 v254, v91, v254
	v_exp_f32_e32 v76, v76
	v_exp_f32_e32 v92, v92
	ds_read_b128 v[228:231], v112 offset:4096
	s_waitcnt lgkmcnt(3)
	v_mfma_f32_32x32x16_bf16 v[18:33], v[126:129], v[114:117], v[18:33]
	v_add_f32_e32 v254, v76, v254
	v_add_f32_e32 v254, v92, v254
	v_exp_f32_e32 v77, v77
	v_fma_f32 v112, v200, s76, v224
	v_fma_f32 v113, v200, s77, v224
	v_add_u32_e32 v179, v183, v208
	ds_read_b128 v[236:239], v179
	s_waitcnt lgkmcnt(3)
	v_mfma_f32_32x32x16_bf16 v[2:17], v[118:121], v[114:117], v[2:17]
	v_add_f32_e64 v114, v240, v98
	v_add_f32_e64 v115, v240, v99
	v_add_f32_e64 v128, v240, v112
	v_add_f32_e64 v129, v240, v113
	v_add_f32_e64 v126, v240, v110
	v_add_f32_e64 v127, v240, v111
	v_add_f32_e32 v124, v240, v108
	v_add_f32_e32 v125, v240, v109
	v_add_f32_e32 v122, v240, v106
	v_add_f32_e32 v123, v240, v107
	v_add_f32_e32 v120, v240, v104
	v_add_f32_e32 v121, v240, v105
	v_add_f32_e32 v118, v240, v102
	v_add_f32_e32 v119, v240, v103
	v_add_f32_e32 v116, v240, v100
	v_add_f32_e32 v117, v240, v101
	ds_read_b128 v[240:243], v179 offset:4096
	s_waitcnt lgkmcnt(3)
	v_mfma_f32_32x32x16_bf16 v[98:113], v[232:235], v[130:133], v[98:113]
	v_add_f32_e32 v254, v77, v254
	v_exp_f32_e32 v93, v93
	v_exp_f32_e32 v78, v78
	v_add_u32_e32 v179, v183, v209
	ds_read_b128 v[232:235], v179
	s_waitcnt lgkmcnt(3)
	v_mfma_f32_32x32x16_bf16 v[114:129], v[228:231], v[130:133], v[114:129]
	v_add_f32_e32 v254, v93, v254
	v_add_f32_e32 v254, v78, v254
	v_exp_f32_e32 v94, v94
	v_exp_f32_e32 v79, v79
	ds_read_b128 v[228:231], v179 offset:4096
	s_waitcnt lgkmcnt(3)
	v_mfma_f32_32x32x16_bf16 v[98:113], v[236:239], v[134:137], v[98:113]
	v_add_f32_e32 v254, v94, v254
	v_add_f32_e32 v254, v79, v254
	v_exp_f32_e32 v95, v95
	v_exp_f32_e32 v80, v80
	v_add_u32_e32 v179, v183, v226
	ds_read_b128 v[236:239], v179
	s_waitcnt lgkmcnt(3)
	v_mfma_f32_32x32x16_bf16 v[114:129], v[240:243], v[134:137], v[114:129]
	v_add_f32_e32 v254, v95, v254
	v_add_f32_e32 v254, v80, v254
	v_exp_f32_e32 v96, v96
	v_exp_f32_e32 v81, v81
	ds_read_b128 v[240:243], v179 offset:4096
	s_waitcnt lgkmcnt(3)
	v_mfma_f32_32x32x16_bf16 v[98:113], v[232:235], v[138:141], v[98:113]
	v_add_f32_e32 v254, v96, v254
	v_add_f32_e32 v254, v81, v254
	v_exp_f32_e32 v97, v97
	s_waitcnt lgkmcnt(2)
	v_mfma_f32_32x32x16_bf16 v[114:129], v[228:231], v[138:141], v[114:129]
	v_add_f32_e32 v254, v97, v254
	s_waitcnt lgkmcnt(1)
	v_mfma_f32_32x32x16_bf16 v[98:113], v[236:239], v[142:145], v[98:113]
	s_waitcnt lgkmcnt(0)
	v_mfma_f32_32x32x16_bf16 v[114:129], v[240:243], v[142:145], v[114:129]
	s_andn2_b64 vcc, exec, s[4:5]
	s_mov_b64 s[4:5], -1
	s_cbranch_vccz .LBB0_470
	s_andn2_b64 vcc, exec, s[4:5]
	s_cbranch_vccz .LBB0_471

.LBB0_462:
	v_add_f32_e32 v179, v198, v254
	s_mov_b64 s[2:3], 0
	s_cmp_lg_u32 s99, 0
	s_cbranch_scc1 .LBB0_464
	s_nop 7
	v_max3_f32 v84, v98, v99, v114
	v_max3_f32 v85, v100, v101, v115
	s_nop 0
	v_max3_f32 v84, v84, v116, v117
	v_max3_f32 v85, v85, v104, v105
	s_nop 0
	v_max3_f32 v84, v84, v102, v103
	v_max3_f32 v85, v85, v120, v121
	s_nop 0
	v_max3_f32 v84, v84, v118, v119
	v_max3_f32 v85, v85, v108, v109
	s_nop 0
	v_max3_f32 v84, v84, v106, v107
	v_max3_f32 v85, v85, v124, v125
	s_nop 0
	v_max3_f32 v84, v84, v122, v123
	v_max3_f32 v85, v85, v112, v113
	s_nop 0
	v_max3_f32 v84, v84, v110, v111
	v_max3_f32 v85, v85, v128, v129
	s_nop 0
	v_max3_f32 v84, v84, v126, v127
	s_nop 0
	v_max_f32_e32 v84, v84, v85
	s_nop 0
	v_mov_b32_e32 v85, v84
	s_nop 1
	v_permlane32_swap_b32 v84, v85
	s_nop 1
	s_nop 0
	v_max_f32_e32 v85, v85, v85
	v_max_f32_e32 v84, v84, v84
	v_max_f32_e32 v84, v84, v85
	v_cmp_lt_f32_e32 vcc, s56, v84
	s_cmp_lg_u64 vcc, 0
	s_cselect_b64 s[2:3], -1, 0
	s_cbranch_vccz .LBB0_464
	v_max_f32_e32 v0, v84, v84
	v_max_f32_e32 v84, 0, v0
	v_exp_f32_e64 v0, -v84
	v_add_f32_e32 v199, v199, v84
	v_pk_add_f32 v[98:99], v[98:99], v[84:85] op_sel_hi:[1,0] neg_lo:[0,1] neg_hi:[0,1]
	v_pk_add_f32 v[114:115], v[114:115], v[84:85] op_sel_hi:[1,0] neg_lo:[0,1] neg_hi:[0,1]
	v_pk_add_f32 v[100:101], v[100:101], v[84:85] op_sel_hi:[1,0] neg_lo:[0,1] neg_hi:[0,1]
	v_pk_add_f32 v[116:117], v[116:117], v[84:85] op_sel_hi:[1,0] neg_lo:[0,1] neg_hi:[0,1]
	v_pk_add_f32 v[102:103], v[102:103], v[84:85] op_sel_hi:[1,0] neg_lo:[0,1] neg_hi:[0,1]
	v_pk_add_f32 v[118:119], v[118:119], v[84:85] op_sel_hi:[1,0] neg_lo:[0,1] neg_hi:[0,1]
	v_pk_add_f32 v[104:105], v[104:105], v[84:85] op_sel_hi:[1,0] neg_lo:[0,1] neg_hi:[0,1]
	v_pk_add_f32 v[120:121], v[120:121], v[84:85] op_sel_hi:[1,0] neg_lo:[0,1] neg_hi:[0,1]
	v_pk_add_f32 v[106:107], v[106:107], v[84:85] op_sel_hi:[1,0] neg_lo:[0,1] neg_hi:[0,1]
	v_pk_add_f32 v[122:123], v[122:123], v[84:85] op_sel_hi:[1,0] neg_lo:[0,1] neg_hi:[0,1]
	v_pk_add_f32 v[108:109], v[108:109], v[84:85] op_sel_hi:[1,0] neg_lo:[0,1] neg_hi:[0,1]
	v_pk_add_f32 v[124:125], v[124:125], v[84:85] op_sel_hi:[1,0] neg_lo:[0,1] neg_hi:[0,1]
	v_pk_add_f32 v[110:111], v[110:111], v[84:85] op_sel_hi:[1,0] neg_lo:[0,1] neg_hi:[0,1]
	v_pk_add_f32 v[126:127], v[126:127], v[84:85] op_sel_hi:[1,0] neg_lo:[0,1] neg_hi:[0,1]
	v_pk_add_f32 v[112:113], v[112:113], v[84:85] op_sel_hi:[1,0] neg_lo:[0,1] neg_hi:[0,1]
	v_pk_add_f32 v[128:129], v[128:129], v[84:85] op_sel_hi:[1,0] neg_lo:[0,1] neg_hi:[0,1]
	v_mul_f32_e32 v179, v179, v0
.LBB0_464:
	s_add_i32 s4, s62, 1
	s_cmp_lg_u32 s62, 2
	s_cselect_b32 s4, s4, 0
	s_add_i32 s5, s10, 1
	s_cmp_lg_u32 s10, 2
	s_cselect_b32 s5, s5, 0
	s_lshl_b32 s62, s5, 14
	v_add_u32_e32 v198, s62, v219
	v_cvt_pk_bf16_f32 v66, v66, v67
	v_cvt_pk_bf16_f32 v67, v68, v69
	v_cvt_pk_bf16_f32 v68, v70, v71
	v_add_u32_e32 v70, v198, v149
	v_cvt_pk_bf16_f32 v69, v82, v83
	v_cvt_pk_bf16_f32 v74, v74, v75
	v_cvt_pk_bf16_f32 v75, v76, v77
	v_cvt_pk_bf16_f32 v76, v78, v79
	v_cvt_pk_bf16_f32 v77, v80, v81
	ds_read_b128 v[78:81], v70 offset:49152
	ds_read_b128 v[82:85], v70 offset:53248
	ds_read_b128 v[86:89], v70 offset:57344
	ds_read_b128 v[228:231], v70 offset:61440
	s_lshl_b32 s10, s4, 14
	s_cmp_gt_i32 s34, s48
	s_waitcnt lgkmcnt(3)
	v_mfma_f32_32x32x16_bf16 v[50:65], v[78:81], v[66:69], v[50:65]
	v_add_u32_e32 v70, v198, v208
	ds_read_b128 v[78:81], v70 offset:49152
	s_waitcnt lgkmcnt(3)
	v_mfma_f32_32x32x16_bf16 v[34:49], v[82:85], v[66:69], v[34:49]
	ds_read_b128 v[232:235], v70 offset:53248
	s_waitcnt lgkmcnt(3)
	v_mfma_f32_32x32x16_bf16 v[18:33], v[86:89], v[66:69], v[18:33]
	ds_read_b128 v[86:89], v70 offset:57344
	s_waitcnt lgkmcnt(3)
	v_mfma_f32_32x32x16_bf16 v[2:17], v[228:231], v[66:69], v[2:17]
	ds_read_b128 v[82:85], v70 offset:61440
	s_waitcnt lgkmcnt(3)
	v_mfma_f32_32x32x16_bf16 v[50:65], v[78:81], v[74:77], v[50:65]
	v_add_u32_e32 v227, v198, v209
	ds_read_b128 v[78:81], v227 offset:49152
	s_waitcnt lgkmcnt(3)
	v_mfma_f32_32x32x16_bf16 v[34:49], v[232:235], v[74:77], v[34:49]
	s_cbranch_scc1 .LBB0_466
	s_cmp_lt_i32 s61, s39
	s_movk_i32 s79, 0xc0
	s_cselect_b32 s79, s79, 0x140
	s_add_i32 s80, s60, s79
	s_ashr_i32 s81, s80, 31
	s_lshl_b64 s[80:81], s[80:81], 12
	s_add_i32 s60, s10, 0xffffc000
	s_cmp_lg_u32 s4, 0
	s_cselect_b32 s60, s60, 0x8000
	v_lshl_add_u64 v[66:67], v[202:203], 0, s[80:81]
	s_add_i32 s60, s7, s60
	v_lshl_add_u64 v[68:69], v[66:67], 0, s[30:31]
	s_mov_b32 m0, s60
	v_lshl_add_u64 v[66:67], v[66:67], 0, s[36:37]
	global_load_lds_dwordx4 v[68:69], off
	s_add_i32 m0, s60, 0x2000
	s_nop 0
	global_load_lds_dwordx4 v[66:67], off
.LBB0_466:
	s_cmp_lt_i32 s78, s39
	s_cselect_b64 s[80:81], -1, 0
	v_cndmask_b32_e64 v228, -v201, v201, s[80:81]
	s_and_b64 s[80:81], s[80:81], exec
	s_cselect_b32 s60, s78, s61
	s_add_i32 s60, s60, s33
	s_lshl_b32 s78, s60, 6
	s_ashr_i32 s79, s78, 31
	s_lshl_b64 s[80:81], s[78:79], 1
	s_addk_i32 s62, 0xc000
	s_cmp_lg_u32 s5, 0
	s_cselect_b32 s60, s62, 0x8000
	s_add_i32 s60, s14, s60
	v_lshl_add_u64 v[66:67], v[204:205], 0, s[80:81]
	s_add_i32 m0, s60, 0xc000
	v_lshl_add_u64 v[68:69], v[206:207], 0, s[80:81]
	global_load_lds_dwordx4 v[66:67], off
	s_add_i32 m0, s60, 0xc400
	v_cvt_f32_i32_e32 v66, s78
	global_load_lds_dwordx4 v[68:69], off
	v_exp_f32_e32 v231, v98
	v_add_f32_e32 v66, v155, v66
	v_fma_f32 v230, v228, v66, -v199
	v_add_u32_e32 v229, s10, v218
	v_exp_f32_e32 v233, v114
	v_fma_f32 v66, 0, v228, v230
	v_exp_f32_e32 v234, v99
	v_exp_f32_e32 v235, v115
	v_add_f32_e32 v67, v228, v230
	v_exp_f32_e32 v236, v100
	v_exp_f32_e32 v237, v116
	v_exp_f32_e32 v238, v101
	v_exp_f32_e32 v239, v117
	v_fma_f32 v68, v228, s64, v230
	v_fma_f32 v69, v228, s65, v230
	v_fma_f32 v70, v228, s66, v230
	v_fma_f32 v71, v228, s67, v230
	v_cvt_pk_bf16_f32 v98, v249, v250
	v_cvt_pk_bf16_f32 v99, v195, v251
	v_cvt_pk_bf16_f32 v100, v252, v253
	v_cvt_pk_bf16_f32 v101, v72, v73
	v_cvt_pk_bf16_f32 v114, v90, v91
	v_cvt_pk_bf16_f32 v115, v92, v93
	v_cvt_pk_bf16_f32 v116, v94, v95
	v_cvt_pk_bf16_f32 v117, v96, v97
	v_mul_f32_e32 v232, 0x42000000, v228
	v_exp_f32_e32 v240, v102
	v_exp_f32_e32 v241, v118
	v_exp_f32_e32 v242, v103
	v_exp_f32_e32 v243, v119
	ds_read_b128 v[90:93], v227 offset:53248
	s_waitcnt lgkmcnt(3)
	v_mfma_f32_32x32x16_bf16 v[18:33], v[86:89], v[74:77], v[18:33]
	v_fma_f32 v72, v228, s68, v230
	v_fma_f32 v73, v228, s69, v230
	v_exp_f32_e32 v181, v104
	v_exp_f32_e32 v183, v120
	ds_read_b128 v[86:89], v227 offset:57344
	s_waitcnt lgkmcnt(3)
	v_mfma_f32_32x32x16_bf16 v[2:17], v[82:85], v[74:77], v[2:17]
	v_exp_f32_e32 v195, v105
	v_exp_f32_e32 v200, v121
	ds_read_b128 v[82:85], v227 offset:61440
	s_waitcnt lgkmcnt(3)
	v_mfma_f32_32x32x16_bf16 v[50:65], v[78:81], v[98:101], v[50:65]
	v_fma_f32 v74, v228, s70, v230
	v_fma_f32 v75, v228, s71, v230
	v_exp_f32_e32 v224, v106
	v_exp_f32_e32 v122, v122
	v_add_u32_e32 v78, v198, v226
	ds_read_b128 v[94:97], v78 offset:49152
	s_waitcnt lgkmcnt(3)
	v_mfma_f32_32x32x16_bf16 v[34:49], v[90:93], v[98:101], v[34:49]
	v_exp_f32_e32 v225, v107
	v_exp_f32_e32 v123, v123
	ds_read_b128 v[90:93], v78 offset:53248
	s_waitcnt lgkmcnt(3)
	v_mfma_f32_32x32x16_bf16 v[18:33], v[86:89], v[98:101], v[18:33]
	v_fma_f32 v76, v228, s72, v230
	v_fma_f32 v77, v228, s73, v230
	v_exp_f32_e32 v227, v108
	v_exp_f32_e32 v124, v124
	ds_read_b128 v[86:89], v78 offset:57344
	s_waitcnt lgkmcnt(3)
	v_mfma_f32_32x32x16_bf16 v[2:17], v[82:85], v[98:101], v[2:17]
	v_exp_f32_e32 v244, v109
	v_exp_f32_e32 v125, v125
	ds_read_b128 v[98:101], v78 offset:61440
	s_waitcnt lgkmcnt(3)
	v_mfma_f32_32x32x16_bf16 v[50:65], v[94:97], v[114:117], v[50:65]
	v_fma_f32 v78, v228, s74, v230
	v_fma_f32 v79, v228, s75, v230
	v_exp_f32_e32 v245, v110
	v_exp_f32_e32 v126, v126
	v_add_u32_e32 v80, v229, v149
	ds_read_b128 v[102:105], v80
	s_waitcnt lgkmcnt(3)
	v_mfma_f32_32x32x16_bf16 v[34:49], v[90:93], v[114:117], v[34:49]
	v_exp_f32_e32 v246, v111
	v_exp_f32_e32 v127, v127
	ds_read_b128 v[106:109], v80 offset:4096
	s_waitcnt lgkmcnt(3)
	v_mfma_f32_32x32x16_bf16 v[18:33], v[86:89], v[114:117], v[18:33]
	v_fma_f32 v80, v228, s76, v230
	v_fma_f32 v81, v228, s77, v230
	v_exp_f32_e32 v247, v112
	v_exp_f32_e32 v128, v128
	v_add_u32_e32 v110, v229, v208
	ds_read_b128 v[118:121], v110
	s_waitcnt lgkmcnt(3)
	v_mfma_f32_32x32x16_bf16 v[2:17], v[98:101], v[114:117], v[2:17]
	v_add_f32_e64 v82, v232, v66
	v_add_f32_e64 v83, v232, v67
	v_add_f32_e64 v96, v232, v80
	v_add_f32_e64 v97, v232, v81
	v_add_f32_e64 v94, v232, v78
	v_add_f32_e64 v95, v232, v79
	v_add_f32_e32 v92, v232, v76
	v_add_f32_e32 v93, v232, v77
	v_add_f32_e32 v90, v232, v74
	v_add_f32_e32 v91, v232, v75
	v_add_f32_e32 v88, v232, v72
	v_add_f32_e32 v89, v232, v73
	v_add_f32_e32 v86, v232, v70
	v_add_f32_e32 v87, v232, v71
	v_add_f32_e32 v84, v232, v68
	v_add_f32_e32 v85, v232, v69
	v_exp_f32_e32 v228, v113
	v_exp_f32_e32 v129, v129
	ds_read_b128 v[98:101], v110 offset:4096
	s_waitcnt lgkmcnt(3)
	v_mfma_f32_32x32x16_bf16 v[66:81], v[102:105], v[130:133], v[66:81]
	v_add_u32_e32 v110, v229, v209
	ds_read_b128 v[102:105], v110
	s_waitcnt lgkmcnt(3)
	v_mfma_f32_32x32x16_bf16 v[82:97], v[106:109], v[130:133], v[82:97]
	ds_read_b128 v[106:109], v110 offset:4096
	s_waitcnt lgkmcnt(3)
	v_mfma_f32_32x32x16_bf16 v[66:81], v[118:121], v[134:137], v[66:81]
	v_add_u32_e32 v114, v229, v226
	ds_read_b128 v[110:113], v114
	s_waitcnt lgkmcnt(3)
	v_mfma_f32_32x32x16_bf16 v[82:97], v[98:101], v[134:137], v[82:97]
	ds_read_b128 v[98:101], v114 offset:4096
	s_waitcnt lgkmcnt(3)
	v_mfma_f32_32x32x16_bf16 v[66:81], v[102:105], v[138:141], v[66:81]
	s_waitcnt lgkmcnt(2)
	v_mfma_f32_32x32x16_bf16 v[82:97], v[106:109], v[138:141], v[82:97]
	s_waitcnt lgkmcnt(1)
	v_mfma_f32_32x32x16_bf16 v[66:81], v[110:113], v[142:145], v[66:81]
	v_add_f32_e32 v102, 0, v231
	v_add_f32_e32 v102, v233, v102
	v_add_f32_e32 v102, v234, v102
	v_add_f32_e32 v102, v235, v102
	v_add_f32_e32 v102, v236, v102
	v_add_f32_e32 v102, v237, v102
	s_waitcnt lgkmcnt(0)
	v_mfma_f32_32x32x16_bf16 v[82:97], v[98:101], v[142:145], v[82:97]
	v_add_f32_e32 v98, v238, v102
	v_add_f32_e32 v98, v239, v98
	v_add_f32_e32 v98, v240, v98
	v_add_f32_e32 v98, v241, v98
	v_add_f32_e32 v98, v242, v98
	v_add_f32_e32 v98, v243, v98
	v_add_f32_e32 v98, v181, v98
	v_add_f32_e32 v98, v183, v98
	v_add_f32_e32 v98, v195, v98
	v_add_f32_e32 v98, v200, v98
	v_add_f32_e32 v98, v224, v98
	v_add_f32_e32 v98, v122, v98
	v_add_f32_e32 v98, v225, v98
	v_add_f32_e32 v98, v123, v98
	v_add_f32_e32 v98, v227, v98
	v_add_f32_e32 v98, v124, v98
	v_add_f32_e32 v98, v244, v98
	v_add_f32_e32 v98, v125, v98
	v_add_f32_e32 v98, v245, v98
	v_add_f32_e32 v98, v126, v98
	v_add_f32_e32 v98, v246, v98
	v_add_f32_e32 v98, v127, v98
	v_add_f32_e32 v98, v247, v98
	v_add_f32_e32 v98, v128, v98
	v_add_f32_e32 v98, v228, v98
	v_add_f32_e32 v98, v129, v98
	s_add_i32 s10, s4, 1
	s_cmp_lg_u32 s4, 2
	s_cselect_b32 s62, s10, 0
	s_add_i32 s4, s5, 1
	s_cmp_lg_u32 s5, 2
	s_cselect_b32 s10, s4, 0
	s_add_i32 s34, s34, 2
	v_add_f32_e32 v198, v179, v98
	v_cvt_pk_bf16_f32 v98, v231, v234
	v_cvt_pk_bf16_f32 v99, v236, v238
	v_cvt_pk_bf16_f32 v100, v240, v242
	v_cvt_pk_bf16_f32 v101, v181, v195
	v_cvt_pk_bf16_f32 v110, v233, v235
	v_cvt_pk_bf16_f32 v111, v237, v239
	v_cvt_pk_bf16_f32 v112, v241, v243
	v_cvt_pk_bf16_f32 v113, v183, v200
	v_cvt_pk_bf16_f32 v106, v224, v225
	v_cvt_pk_bf16_f32 v107, v227, v244
	v_cvt_pk_bf16_f32 v108, v245, v246
	v_cvt_pk_bf16_f32 v109, v247, v228
	v_cvt_pk_bf16_f32 v114, v122, v123
	v_cvt_pk_bf16_f32 v115, v124, v125
	v_cvt_pk_bf16_f32 v116, v126, v127
	s_cmp_ge_i32 s61, s48
	v_cvt_pk_bf16_f32 v117, v128, v129
	s_cbranch_scc1 .LBB0_473
	s_mov_b32 s60, s63
	s_add_i32 s61, s34, -2
	s_cmp_gt_i32 s61, s48
	s_mov_b64 s[4:5], -1
	s_cbranch_scc1 .LBB0_451

	.amdhsa_kernel _Z9hymba_fwd4Args
		.amdhsa_group_segment_fixed_size 0
		.amdhsa_private_segment_fixed_size 0
		.amdhsa_kernarg_size 376
		.amdhsa_user_sgpr_count 2
		.amdhsa_user_sgpr_dispatch_ptr 0
		.amdhsa_user_sgpr_queue_ptr 0
		.amdhsa_user_sgpr_kernarg_segment_ptr 1
		.amdhsa_user_sgpr_dispatch_id 0
		.amdhsa_user_sgpr_kernarg_preload_length 0
		.amdhsa_user_sgpr_kernarg_preload_offset 0
		.amdhsa_user_sgpr_private_segment_size 0
		.amdhsa_uses_dynamic_stack 0
		.amdhsa_enable_private_segment 0
		.amdhsa_system_sgpr_workgroup_id_x 1
		.amdhsa_system_sgpr_workgroup_id_y 0
		.amdhsa_system_sgpr_workgroup_id_z 0
		.amdhsa_system_sgpr_workgroup_info 0
		.amdhsa_system_vgpr_workitem_id 2
		.amdhsa_next_free_vgpr 256
		.amdhsa_next_free_sgpr 100
		.amdhsa_accum_offset 256
		.amdhsa_reserve_vcc 1
		.amdhsa_float_round_mode_32 0
		.amdhsa_float_round_mode_16_64 0
		.amdhsa_float_denorm_mode_32 3
		.amdhsa_float_denorm_mode_16_64 3
		.amdhsa_dx10_clamp 1
		.amdhsa_ieee_mode 1
		.amdhsa_fp16_overflow 0
		.amdhsa_tg_split 0
		.amdhsa_exception_fp_ieee_invalid_op 0
		.amdhsa_exception_fp_denorm_src 0
		.amdhsa_exception_fp_ieee_div_zero 0
		.amdhsa_exception_fp_ieee_overflow 0
		.amdhsa_exception_fp_ieee_underflow 0
		.amdhsa_exception_fp_ieee_inexact 0
		.amdhsa_exception_int_div_zero 0
	.end_amdhsa_kernel

amdhsa.kernels:
  - .agpr_count:     0
    .args:
      - .offset:         0
        .size:           120
        .value_kind:     by_value
      - .offset:         120
        .size:           4
        .value_kind:     hidden_block_count_x
      - .offset:         124
        .size:           4
        .value_kind:     hidden_block_count_y
      - .offset:         128
        .size:           4
        .value_kind:     hidden_block_count_z
      - .offset:         132
        .size:           2
        .value_kind:     hidden_group_size_x
      - .offset:         134
        .size:           2
        .value_kind:     hidden_group_size_y
      - .offset:         136
        .size:           2
        .value_kind:     hidden_group_size_z
      - .offset:         138
        .size:           2
        .value_kind:     hidden_remainder_x
      - .offset:         140
        .size:           2
        .value_kind:     hidden_remainder_y
      - .offset:         142
        .size:           2
        .value_kind:     hidden_remainder_z
      - .offset:         160
        .size:           8
        .value_kind:     hidden_global_offset_x
      - .offset:         168
        .size:           8
        .value_kind:     hidden_global_offset_y
      - .offset:         176
        .size:           8
        .value_kind:     hidden_global_offset_z
      - .offset:         184
        .size:           2
        .value_kind:     hidden_grid_dims
      - .offset:         208
        .size:           8
        .value_kind:     hidden_multigrid_sync_arg
      - .offset:         240
        .size:           4
        .value_kind:     hidden_dynamic_lds_size
    .group_segment_fixed_size: 0
    .kernarg_segment_align: 8
    .kernarg_segment_size: 376
    .language:       OpenCL C
    .language_version:
      - 2
      - 0
    .max_flat_workgroup_size: 512
    .name:           _Z9hymba_fwd4Args
    .private_segment_fixed_size: 0
    .sgpr_count:     106
    .sgpr_spill_count: 36
    .symbol:         _Z9hymba_fwd4Args.kd
    .uniform_work_group_size: 1
    .uses_dynamic_stack: false
    .vgpr_count:     256
    .vgpr_spill_count: 0
    .wavefront_size: 64
